# prep K.K^T strip reads batched and chains interleaved; w_dn[0] transposes in the first up-projection tail: all 32 source loads of an item in flight
# speedup vs baseline: 1.0209x; 1.0017x over previous
; template <class Map>
; __device__ __forceinline__ void transpose_item(const float* W, int K, int N, bf16_t* WT, float* scr, int item, int nblk, int lane, Map srccol) {
;     const int kb = item / nblk, nb = item % nblk, k0 = 64 * kb, n0 = 32 * nb;
;     const int sc = srccol(n0 + (lane & 31));
;     float tv[32];
;     const float* wp = W + (size_t)(k0 + (lane >> 5)) * N + (sc >= 0 ? sc : 0);
; #pragma unroll
;     for (int i = 0; i < 32; ++i) tv[i] = wp[(size_t)(2 * i) * N];
; #pragma unroll
;     for (int i = 0; i < 32; ++i) { const int kk = 2 * i + (lane >> 5); scr[kk * 33 + (lane & 31)] = sc >= 0 ? tv[i] : 0.f; }
.LBB0_218:
	s_ashr_i32 s6, s19, 31
	s_lshr_b32 s6, s6, 27
	s_add_i32 s6, s19, s6
	s_ashr_i32 s22, s6, 5
	s_andn2_b32 s6, s6, 31
	s_lshl_b32 s10, s22, 6
	s_lshl_b32 s7, s22, 10
	s_sub_i32 s6, s19, s6
	v_subrev_u32_e32 v0, s7, v13
	v_or_b32_e32 v16, s10, v6
	v_and_b32_e32 v15, 24, v14
	v_and_b32_e32 v0, 0xffffffe3, v0
	v_ashrrev_i32_e32 v17, 31, v16
	s_cmp_gt_i32 s6, -1
	v_or3_b32 v0, v0, v9, v15
	v_lshlrev_b64 v[16:17], 12, v[16:17]
	s_cselect_b64 vcc, -1, 0
	v_lshl_add_u64 v[16:17], s[2:3], 0, v[16:17]
	v_cndmask_b32_e32 v0, 0, v0, vcc
	v_lshl_add_u64 v[40:41], v[0:1], 2, v[16:17]
	v_add_co_u32_e64 v16, s[6:7], s63, v40
	global_load_dword v44, v[40:41], off
	s_nop 0
	v_addc_co_u32_e64 v17, s[6:7], 0, v41, s[6:7]
	global_load_dword v45, v[16:17], off
	v_add_co_u32_e64 v16, s[6:7], s23, v40
	s_mul_i32 s22, s22, 0xffd40000
	s_nop 0
	v_addc_co_u32_e64 v17, s[6:7], 0, v41, s[6:7]
	global_load_dword v46, v[16:17], off
	v_add_co_u32_e64 v16, s[6:7], s58, v40
	s_ashr_i32 s11, s10, 31
	s_nop 0
	v_addc_co_u32_e64 v17, s[6:7], 0, v41, s[6:7]
	global_load_dword v47, v[16:17], off
	v_add_co_u32_e64 v16, s[6:7], s60, v40
	s_add_i32 s19, s19, s13
	s_nop 0
	v_addc_co_u32_e64 v17, s[6:7], 0, v41, s[6:7]
	global_load_dword v48, v[16:17], off
	v_add_co_u32_e64 v16, s[6:7], s26, v40
	v_add_u32_e32 v13, s20, v13
	s_nop 0
	v_addc_co_u32_e64 v17, s[6:7], 0, v41, s[6:7]
	global_load_dword v49, v[16:17], off
	v_add_co_u32_e64 v16, s[6:7], s29, v40
	v_add_u32_e32 v14, s21, v14
	s_nop 0
	v_addc_co_u32_e64 v17, s[6:7], 0, v41, s[6:7]
	global_load_dword v36, v[16:17], off
	v_add_co_u32_e64 v16, s[6:7], s30, v40
	s_cmpk_gt_i32 s19, 0x57f
	s_nop 0
	v_addc_co_u32_e64 v17, s[6:7], 0, v41, s[6:7]
	global_load_dword v37, v[16:17], off
	v_add_co_u32_e64 v16, s[6:7], s24, v40
	s_nop 1
	v_addc_co_u32_e64 v17, s[6:7], 0, v41, s[6:7]
	global_load_dword v38, v[16:17], off
	v_add_co_u32_e64 v16, s[6:7], s55, v40
	s_nop 1
	v_addc_co_u32_e64 v17, s[6:7], 0, v41, s[6:7]
	global_load_dword v39, v[16:17], off
	v_add_co_u32_e64 v16, s[6:7], s56, v40
	s_nop 1
	v_addc_co_u32_e64 v17, s[6:7], 0, v41, s[6:7]
	global_load_dword v32, v[16:17], off
	v_add_co_u32_e64 v16, s[6:7], s57, v40
	s_nop 1
	v_addc_co_u32_e64 v17, s[6:7], 0, v41, s[6:7]
	global_load_dword v33, v[16:17], off
	v_add_co_u32_e64 v16, s[6:7], s59, v40
	s_nop 1
	v_addc_co_u32_e64 v17, s[6:7], 0, v41, s[6:7]
	global_load_dword v34, v[16:17], off
	v_add_co_u32_e64 v16, s[6:7], s25, v40
	s_nop 1
	v_addc_co_u32_e64 v17, s[6:7], 0, v41, s[6:7]
	global_load_dword v35, v[16:17], off
	v_add_co_u32_e64 v16, s[6:7], s27, v40
	s_nop 1
	v_addc_co_u32_e64 v17, s[6:7], 0, v41, s[6:7]
	global_load_dword v28, v[16:17], off
	v_add_co_u32_e64 v16, s[6:7], s28, v40
	s_nop 1
	v_addc_co_u32_e64 v17, s[6:7], 0, v41, s[6:7]
	global_load_dword v29, v[16:17], off
	v_add_co_u32_e64 v16, s[6:7], s31, v40
	s_nop 1
	v_addc_co_u32_e64 v17, s[6:7], 0, v41, s[6:7]
	global_load_dword v30, v[16:17], off
	v_add_co_u32_e64 v16, s[6:7], s34, v40
	s_nop 1
	v_addc_co_u32_e64 v17, s[6:7], 0, v41, s[6:7]
	global_load_dword v31, v[16:17], off
	v_add_co_u32_e64 v16, s[6:7], s35, v40
	s_nop 1
	v_addc_co_u32_e64 v17, s[6:7], 0, v41, s[6:7]
	global_load_dword v24, v[16:17], off
	v_add_co_u32_e64 v16, s[6:7], s1, v40
	s_nop 1
	v_addc_co_u32_e64 v17, s[6:7], 0, v41, s[6:7]
	global_load_dword v25, v[16:17], off
	v_add_co_u32_e64 v16, s[6:7], s40, v40
	s_nop 1
	v_addc_co_u32_e64 v17, s[6:7], 0, v41, s[6:7]
	global_load_dword v26, v[16:17], off
	v_add_co_u32_e64 v16, s[6:7], s41, v40
	s_nop 1
	v_addc_co_u32_e64 v17, s[6:7], 0, v41, s[6:7]
	global_load_dword v27, v[16:17], off
	v_add_co_u32_e64 v16, s[6:7], s33, v40
	s_nop 1
	v_addc_co_u32_e64 v17, s[6:7], 0, v41, s[6:7]
	global_load_dword v20, v[16:17], off
	v_add_co_u32_e64 v16, s[6:7], s44, v40
	s_nop 1
	v_addc_co_u32_e64 v17, s[6:7], 0, v41, s[6:7]
	global_load_dword v21, v[16:17], off
	v_add_co_u32_e64 v16, s[6:7], s0, v40
	s_nop 1
	v_addc_co_u32_e64 v17, s[6:7], 0, v41, s[6:7]
	global_load_dword v22, v[16:17], off
	v_add_co_u32_e64 v16, s[6:7], s45, v40
	s_nop 1
	v_addc_co_u32_e64 v17, s[6:7], 0, v41, s[6:7]
	global_load_dword v23, v[16:17], off
	v_add_co_u32_e64 v16, s[6:7], s46, v40
	s_nop 1
	v_addc_co_u32_e64 v17, s[6:7], 0, v41, s[6:7]
	v_add_co_u32_e64 v18, s[6:7], s47, v40
	global_load_dword v16, v[16:17], off
	s_nop 0
	v_addc_co_u32_e64 v19, s[6:7], 0, v41, s[6:7]
	global_load_dword v17, v[18:19], off
	v_add_co_u32_e64 v18, s[6:7], s48, v40
	s_nop 1
	v_addc_co_u32_e64 v19, s[6:7], 0, v41, s[6:7]
	v_add_co_u32_e64 v42, s[6:7], s49, v40
	global_load_dword v18, v[18:19], off
	s_nop 0
	v_addc_co_u32_e64 v43, s[6:7], 0, v41, s[6:7]
	global_load_dword v19, v[42:43], off
	v_add_co_u32_e64 v42, s[6:7], s50, v40
	s_nop 1
	v_addc_co_u32_e64 v43, s[6:7], 0, v41, s[6:7]
	v_add_co_u32_e64 v40, s[6:7], s52, v40
	global_load_dword v0, v[42:43], off
	s_nop 0
	v_addc_co_u32_e64 v41, s[6:7], 0, v41, s[6:7]
	global_load_dword v15, v[40:41], off
	s_waitcnt vmcnt(0)
; __device__ __forceinline__ unsigned pk2(float lo, float hi) { unsigned r; asm("v_cvt_pk_bf16_f32 %0, %1, %2" : "=v"(r) : "v"(lo), "v"(hi)); return r; }
; template <class Map>
; __device__ __forceinline__ void transpose_item(const float* W, int K, int N, bf16_t* WT, float* scr, int item, int nblk, int lane, Map srccol) {
;     ...
;     for (int i = 0; i < 32; ++i) tv[i] = wp[(size_t)(2 * i) * N];
; #pragma unroll
;     for (int i = 0; i < 32; ++i) { const int kk = 2 * i + (lane >> 5); scr[kk * 33 + (lane & 31)] = sc >= 0 ? tv[i] : 0.f; }
;     __builtin_amdgcn_s_waitcnt(0); asm volatile("" ::: "memory");
;     const int c = lane & 7;
; #pragma unroll
;     for (int j = 0; j < 4; ++j) { const int n = (lane >> 3) + 8 * j; const float* s = scr + (8 * c) * 33 + n;
;         u32x4 o; o.x = pk2(s[0 * 33], s[1 * 33]); o.y = pk2(s[2 * 33], s[3 * 33]); o.z = pk2(s[4 * 33], s[5 * 33]); o.w = pk2(s[6 * 33], s[7 * 33]);
;         *(u32x4*)(WT + (size_t)(n0 + n) * K + k0 + 8 * c) = o; }
;     __builtin_amdgcn_s_waitcnt(0); asm volatile("" ::: "memory");
	v_cndmask_b32_e32 v36, 0, v36, vcc
	v_cndmask_b32_e32 v37, 0, v37, vcc
	v_cndmask_b32_e32 v32, 0, v32, vcc
	v_cndmask_b32_e32 v33, 0, v33, vcc
	v_cndmask_b32_e32 v28, 0, v28, vcc
	v_cndmask_b32_e32 v29, 0, v29, vcc
	v_cndmask_b32_e32 v24, 0, v24, vcc
	v_cndmask_b32_e32 v25, 0, v25, vcc
	v_cndmask_b32_e32 v20, 0, v20, vcc
	v_cndmask_b32_e32 v21, 0, v21, vcc
	v_cndmask_b32_e32 v16, 0, v16, vcc
	v_cndmask_b32_e32 v17, 0, v17, vcc
	v_add_u32_e32 v42, 0x400, v7
	ds_write2_b32 v42, v36, v37 offset0:140 offset1:206
	v_cndmask_b32_e32 v36, 0, v38, vcc
	v_add_u32_e32 v38, 0x800, v7
	ds_write2_b32 v38, v32, v33 offset0:148 offset1:214
	v_cndmask_b32_e32 v32, 0, v34, vcc
	v_add_u32_e32 v34, 0xc00, v7
	ds_write2_b32 v34, v28, v29 offset0:156 offset1:222
	v_cndmask_b32_e32 v28, 0, v30, vcc
	v_add_u32_e32 v30, 0x1000, v7
	v_cndmask_b32_e32 v40, 0, v44, vcc
	v_cndmask_b32_e32 v41, 0, v45, vcc
	ds_write2_b32 v30, v24, v25 offset0:164 offset1:230
	v_cndmask_b32_e32 v24, 0, v26, vcc
	v_add_u32_e32 v26, 0x1400, v7
	ds_write2_b32 v7, v40, v41 offset1:66
	v_cndmask_b32_e32 v40, 0, v46, vcc
	v_cndmask_b32_e32 v41, 0, v47, vcc
	ds_write2_b32 v26, v20, v21 offset0:172 offset1:238
	v_cndmask_b32_e32 v20, 0, v22, vcc
	v_add_u32_e32 v22, 0x1800, v7
	ds_write2_b32 v7, v40, v41 offset0:132 offset1:198
	v_cndmask_b32_e32 v40, 0, v48, vcc
	v_cndmask_b32_e32 v41, 0, v49, vcc
	v_cndmask_b32_e32 v37, 0, v39, vcc
	v_cndmask_b32_e32 v33, 0, v35, vcc
	v_cndmask_b32_e32 v29, 0, v31, vcc
	v_cndmask_b32_e32 v25, 0, v27, vcc
	v_cndmask_b32_e32 v21, 0, v23, vcc
	ds_write2_b32 v22, v16, v17 offset0:180 offset1:246
	ds_write2_b32 v42, v40, v41 offset0:8 offset1:74
	ds_write2_b32 v38, v36, v37 offset0:16 offset1:82
	ds_write2_b32 v34, v32, v33 offset0:24 offset1:90
	ds_write2_b32 v30, v28, v29 offset0:32 offset1:98
	ds_write2_b32 v26, v24, v25 offset0:40 offset1:106
	ds_write2_b32 v22, v20, v21 offset0:48 offset1:114
	v_add_u32_e32 v38, s22, v12
	v_lshl_add_u64 v[20:21], s[10:11], 1, v[2:3]
	v_ashrrev_i32_e32 v39, 31, v38
	v_lshl_add_u64 v[40:41], v[38:39], 1, v[20:21]
	s_mul_i32 s6, s13, 0x16000
	v_add_u32_e32 v12, s6, v12
	s_waitcnt vmcnt(3)
	v_cndmask_b32_e32 v16, 0, v18, vcc
	v_add_u32_e32 v18, 0x1c00, v7
	s_waitcnt vmcnt(2)
	v_cndmask_b32_e32 v17, 0, v19, vcc
	ds_write2_b32 v18, v16, v17 offset0:56 offset1:122
	s_waitcnt vmcnt(1)
	v_cndmask_b32_e32 v0, 0, v0, vcc
	s_waitcnt vmcnt(0)
	v_cndmask_b32_e32 v15, 0, v15, vcc
	ds_write2_b32 v18, v0, v15 offset0:188 offset1:254
	s_waitcnt vmcnt(0) expcnt(0) lgkmcnt(0)
	ds_read2_b32 v[22:23], v8 offset0:33 offset1:41
	ds_read2_b32 v[24:25], v8 offset1:8
	ds_read2_b32 v[26:27], v8 offset0:66 offset1:74
	ds_read2_b32 v[28:29], v8 offset0:99 offset1:107
	ds_read2_b32 v[30:31], v8 offset0:132 offset1:140
	ds_read2_b32 v[32:33], v8 offset0:165 offset1:173
	ds_read2_b32 v[34:35], v8 offset0:198 offset1:206
	ds_read2_b32 v[36:37], v8 offset0:231 offset1:239
	s_waitcnt lgkmcnt(6)
	v_cvt_pk_bf16_f32 v16, v24, v22
	v_add_u32_e32 v22, 0x5800, v38
	s_waitcnt lgkmcnt(4)
	v_cvt_pk_bf16_f32 v17, v26, v28
	s_waitcnt lgkmcnt(2)
	v_cvt_pk_bf16_f32 v18, v30, v32
	s_waitcnt lgkmcnt(0)
	v_cvt_pk_bf16_f32 v19, v34, v36
	global_store_dwordx4 v[40:41], v[16:19], off
	v_add_u32_e32 v40, 0xb000, v38
	v_ashrrev_i32_e32 v41, 31, v40
	v_cvt_pk_bf16_f32 v16, v25, v23
	v_ashrrev_i32_e32 v23, 31, v22
	v_lshl_add_u64 v[22:23], v[22:23], 1, v[20:21]
	v_cvt_pk_bf16_f32 v17, v27, v29
	v_cvt_pk_bf16_f32 v18, v31, v33
	v_cvt_pk_bf16_f32 v19, v35, v37
	global_store_dwordx4 v[22:23], v[16:19], off
	ds_read2_b32 v[22:23], v8 offset0:16 offset1:24
	ds_read2_b32 v[24:25], v8 offset0:49 offset1:57
	ds_read2_b32 v[26:27], v8 offset0:82 offset1:90
	ds_read2_b32 v[28:29], v8 offset0:115 offset1:123
	ds_read2_b32 v[30:31], v8 offset0:148 offset1:156
	ds_read2_b32 v[32:33], v8 offset0:181 offset1:189
	ds_read2_b32 v[34:35], v8 offset0:214 offset1:222
	ds_read2_b32 v[36:37], v8 offset0:247 offset1:255
	s_waitcnt lgkmcnt(6)
	v_cvt_pk_bf16_f32 v16, v22, v24
	v_lshl_add_u64 v[40:41], v[40:41], 1, v[20:21]
	v_add_u32_e32 v22, 0x10800, v38
	s_waitcnt lgkmcnt(4)
	v_cvt_pk_bf16_f32 v17, v26, v28
	s_waitcnt lgkmcnt(2)
	v_cvt_pk_bf16_f32 v18, v30, v32
	s_waitcnt lgkmcnt(0)
	v_cvt_pk_bf16_f32 v19, v34, v36
	global_store_dwordx4 v[40:41], v[16:19], off
	s_nop 1
	v_cvt_pk_bf16_f32 v16, v23, v25
	v_ashrrev_i32_e32 v23, 31, v22
	v_lshl_add_u64 v[20:21], v[22:23], 1, v[20:21]
	v_cvt_pk_bf16_f32 v17, v27, v29
	v_cvt_pk_bf16_f32 v18, v31, v33
	v_cvt_pk_bf16_f32 v19, v35, v37
	global_store_dwordx4 v[20:21], v[16:19], off
	s_waitcnt vmcnt(0) expcnt(0) lgkmcnt(0)
	s_cbranch_scc0 .LBB0_218
	s_branch .LBB0_213

; template <class Map>
; __device__ __forceinline__ void transpose_item(const float* W, int K, int N, bf16_t* WT, float* scr, int item, int nblk, int lane, Map srccol) {
;     const int kb = item / nblk, nb = item % nblk, k0 = 64 * kb, n0 = 32 * nb;
;     const int sc = srccol(n0 + (lane & 31));
;     float tv[32];
;     const float* wp = W + (size_t)(k0 + (lane >> 5)) * N + (sc >= 0 ? sc : 0);
; #pragma unroll
;     for (int i = 0; i < 32; ++i) tv[i] = wp[(size_t)(2 * i) * N];
; #pragma unroll
;     for (int i = 0; i < 32; ++i) { const int kk = 2 * i + (lane >> 5); scr[kk * 33 + (lane & 31)] = sc >= 0 ? tv[i] : 0.f; }
.LBB0_227:
	s_ashr_i32 s6, s13, 31
	s_lshr_b32 s6, s6, 27
	s_add_i32 s6, s13, s6
	s_ashr_i32 s15, s6, 5
	s_lshl_b32 s7, s15, 10
	v_subrev_u32_e32 v0, s7, v12
	s_andn2_b32 s6, s6, 31
	s_lshl_b32 s8, s15, 6
	v_and_b32_e32 v14, 24, v13
	v_and_b32_e32 v0, 0xffffffe3, v0
	s_sub_i32 s6, s13, s6
	v_or3_b32 v0, v0, v8, v14
	v_or_b32_e32 v14, s8, v6
	v_ashrrev_i32_e32 v15, 31, v14
	s_cmp_gt_i32 s6, -1
	v_lshlrev_b64 v[14:15], 12, v[14:15]
	s_cselect_b64 vcc, -1, 0
	v_lshl_add_u64 v[14:15], s[2:3], 0, v[14:15]
	v_cndmask_b32_e32 v0, 0, v0, vcc
	v_lshl_add_u64 v[40:41], v[0:1], 2, v[14:15]
	v_add_co_u32_e64 v14, s[6:7], s63, v40
	global_load_dword v39, v[40:41], off
	s_nop 0
	v_addc_co_u32_e64 v15, s[6:7], 0, v41, s[6:7]
	global_load_dword v44, v[14:15], off
	v_add_co_u32_e64 v14, s[6:7], s22, v40
	s_mul_i32 s15, s15, 0xffd40000
	s_nop 0
	v_addc_co_u32_e64 v15, s[6:7], 0, v41, s[6:7]
	global_load_dword v45, v[14:15], off
	v_add_co_u32_e64 v14, s[6:7], s58, v40
	s_ashr_i32 s9, s8, 31
	s_nop 0
	v_addc_co_u32_e64 v15, s[6:7], 0, v41, s[6:7]
	global_load_dword v46, v[14:15], off
	v_add_co_u32_e64 v14, s[6:7], s60, v40
	s_add_i32 s13, s13, s4
	s_nop 0
	v_addc_co_u32_e64 v15, s[6:7], 0, v41, s[6:7]
	global_load_dword v47, v[14:15], off
	v_add_co_u32_e64 v14, s[6:7], s18, v40
	v_add_u32_e32 v12, s97, v12
	s_nop 0
	v_addc_co_u32_e64 v15, s[6:7], 0, v41, s[6:7]
	global_load_dword v48, v[14:15], off
	v_add_co_u32_e64 v14, s[6:7], s21, v40
	v_add_u32_e32 v13, s14, v13
	s_nop 0
	v_addc_co_u32_e64 v15, s[6:7], 0, v41, s[6:7]
	global_load_dword v35, v[14:15], off
	v_add_co_u32_e64 v14, s[6:7], s23, v40
	s_cmpk_gt_i32 s13, 0x57f
	s_nop 0
	v_addc_co_u32_e64 v15, s[6:7], 0, v41, s[6:7]
	global_load_dword v36, v[14:15], off
	v_add_co_u32_e64 v14, s[6:7], s16, v40
	s_nop 1
	v_addc_co_u32_e64 v15, s[6:7], 0, v41, s[6:7]
	global_load_dword v37, v[14:15], off
	v_add_co_u32_e64 v14, s[6:7], s55, v40
	s_nop 1
	v_addc_co_u32_e64 v15, s[6:7], 0, v41, s[6:7]
	global_load_dword v38, v[14:15], off
	v_add_co_u32_e64 v14, s[6:7], s56, v40
	s_nop 1
	v_addc_co_u32_e64 v15, s[6:7], 0, v41, s[6:7]
	global_load_dword v31, v[14:15], off
	v_add_co_u32_e64 v14, s[6:7], s57, v40
	s_nop 1
	v_addc_co_u32_e64 v15, s[6:7], 0, v41, s[6:7]
	global_load_dword v32, v[14:15], off
	v_add_co_u32_e64 v14, s[6:7], s59, v40
	s_nop 1
	v_addc_co_u32_e64 v15, s[6:7], 0, v41, s[6:7]
	global_load_dword v33, v[14:15], off
	v_add_co_u32_e64 v14, s[6:7], s17, v40
	s_nop 1
	v_addc_co_u32_e64 v15, s[6:7], 0, v41, s[6:7]
	global_load_dword v34, v[14:15], off
	v_add_co_u32_e64 v14, s[6:7], s19, v40
	s_nop 1
	v_addc_co_u32_e64 v15, s[6:7], 0, v41, s[6:7]
	global_load_dword v27, v[14:15], off
	v_add_co_u32_e64 v14, s[6:7], s20, v40
	s_nop 1
	v_addc_co_u32_e64 v15, s[6:7], 0, v41, s[6:7]
	global_load_dword v28, v[14:15], off
	v_add_co_u32_e64 v14, s[6:7], s24, v40
	s_nop 1
	v_addc_co_u32_e64 v15, s[6:7], 0, v41, s[6:7]
	global_load_dword v29, v[14:15], off
	v_add_co_u32_e64 v14, s[6:7], s25, v40
	s_nop 1
	v_addc_co_u32_e64 v15, s[6:7], 0, v41, s[6:7]
	global_load_dword v30, v[14:15], off
	v_add_co_u32_e64 v14, s[6:7], s26, v40
	s_nop 1
	v_addc_co_u32_e64 v15, s[6:7], 0, v41, s[6:7]
	global_load_dword v23, v[14:15], off
	v_add_co_u32_e64 v14, s[6:7], s1, v40
	s_nop 1
	v_addc_co_u32_e64 v15, s[6:7], 0, v41, s[6:7]
	global_load_dword v24, v[14:15], off
	v_add_co_u32_e64 v14, s[6:7], s27, v40
	s_nop 1
	v_addc_co_u32_e64 v15, s[6:7], 0, v41, s[6:7]
	global_load_dword v25, v[14:15], off
	v_add_co_u32_e64 v14, s[6:7], s28, v40
	s_nop 1
	v_addc_co_u32_e64 v15, s[6:7], 0, v41, s[6:7]
	global_load_dword v26, v[14:15], off
	v_add_co_u32_e64 v14, s[6:7], s33, v40
	s_nop 1
	v_addc_co_u32_e64 v15, s[6:7], 0, v41, s[6:7]
	global_load_dword v19, v[14:15], off
	v_add_co_u32_e64 v14, s[6:7], s29, v40
	s_nop 1
	v_addc_co_u32_e64 v15, s[6:7], 0, v41, s[6:7]
	global_load_dword v20, v[14:15], off
	v_add_co_u32_e64 v14, s[6:7], s0, v40
	s_nop 1
	v_addc_co_u32_e64 v15, s[6:7], 0, v41, s[6:7]
	global_load_dword v21, v[14:15], off
	v_add_co_u32_e64 v14, s[6:7], s30, v40
	s_nop 1
	v_addc_co_u32_e64 v15, s[6:7], 0, v41, s[6:7]
	global_load_dword v22, v[14:15], off
	v_add_co_u32_e64 v14, s[6:7], s31, v40
	s_nop 1
	v_addc_co_u32_e64 v15, s[6:7], 0, v41, s[6:7]
	v_add_co_u32_e64 v16, s[6:7], s34, v40
	global_load_dword v15, v[14:15], off
	s_nop 0
	v_addc_co_u32_e64 v17, s[6:7], 0, v41, s[6:7]
	v_add_co_u32_e64 v42, s[6:7], s35, v40
	global_load_dword v16, v[16:17], off
	s_nop 0
	v_addc_co_u32_e64 v43, s[6:7], 0, v41, s[6:7]
	global_load_dword v17, v[42:43], off
	v_add_co_u32_e64 v42, s[6:7], s40, v40
	s_nop 1
	v_addc_co_u32_e64 v43, s[6:7], 0, v41, s[6:7]
	global_load_dword v18, v[42:43], off
	v_add_co_u32_e64 v42, s[6:7], s41, v40
	s_nop 1
	v_addc_co_u32_e64 v43, s[6:7], 0, v41, s[6:7]
	v_add_co_u32_e64 v40, s[6:7], s44, v40
	global_load_dword v0, v[42:43], off
	s_nop 0
	v_addc_co_u32_e64 v41, s[6:7], 0, v41, s[6:7]
	global_load_dword v14, v[40:41], off
	s_waitcnt vmcnt(0)
; __device__ __forceinline__ unsigned pk2(float lo, float hi) { unsigned r; asm("v_cvt_pk_bf16_f32 %0, %1, %2" : "=v"(r) : "v"(lo), "v"(hi)); return r; }
; template <class Map>
; __device__ __forceinline__ void transpose_item(const float* W, int K, int N, bf16_t* WT, float* scr, int item, int nblk, int lane, Map srccol) {
;     ...
;     for (int i = 0; i < 32; ++i) tv[i] = wp[(size_t)(2 * i) * N];
; #pragma unroll
;     for (int i = 0; i < 32; ++i) { const int kk = 2 * i + (lane >> 5); scr[kk * 33 + (lane & 31)] = sc >= 0 ? tv[i] : 0.f; }
;     __builtin_amdgcn_s_waitcnt(0); asm volatile("" ::: "memory");
;     const int c = lane & 7;
; #pragma unroll
;     for (int j = 0; j < 4; ++j) { const int n = (lane >> 3) + 8 * j; const float* s = scr + (8 * c) * 33 + n;
;         u32x4 o; o.x = pk2(s[0 * 33], s[1 * 33]); o.y = pk2(s[2 * 33], s[3 * 33]); o.z = pk2(s[4 * 33], s[5 * 33]); o.w = pk2(s[6 * 33], s[7 * 33]);
;         *(u32x4*)(WT + (size_t)(n0 + n) * K + k0 + 8 * c) = o; }
;     __builtin_amdgcn_s_waitcnt(0); asm volatile("" ::: "memory");
	v_cndmask_b32_e32 v39, 0, v39, vcc
	v_cndmask_b32_e32 v35, 0, v35, vcc
	v_cndmask_b32_e32 v36, 0, v36, vcc
	v_cndmask_b32_e32 v31, 0, v31, vcc
	v_cndmask_b32_e32 v32, 0, v32, vcc
	v_cndmask_b32_e32 v27, 0, v27, vcc
	v_cndmask_b32_e32 v28, 0, v28, vcc
	v_cndmask_b32_e32 v23, 0, v23, vcc
	v_cndmask_b32_e32 v24, 0, v24, vcc
	v_cndmask_b32_e32 v19, 0, v19, vcc
	v_cndmask_b32_e32 v20, 0, v20, vcc
	v_cndmask_b32_e32 v15, 0, v15, vcc
	v_cndmask_b32_e32 v16, 0, v16, vcc
	v_add_u32_e32 v41, 0x400, v7
	ds_write2_b32 v41, v35, v36 offset0:140 offset1:206
	v_cndmask_b32_e32 v35, 0, v37, vcc
	v_add_u32_e32 v37, 0x800, v7
	ds_write2_b32 v37, v31, v32 offset0:148 offset1:214
	v_cndmask_b32_e32 v31, 0, v33, vcc
	v_add_u32_e32 v33, 0xc00, v7
	ds_write2_b32 v33, v27, v28 offset0:156 offset1:222
	v_cndmask_b32_e32 v27, 0, v29, vcc
	v_add_u32_e32 v29, 0x1000, v7
	v_cndmask_b32_e32 v40, 0, v44, vcc
	ds_write2_b32 v29, v23, v24 offset0:164 offset1:230
	v_cndmask_b32_e32 v23, 0, v25, vcc
	v_add_u32_e32 v25, 0x1400, v7
	ds_write2_b32 v7, v39, v40 offset1:66
	v_cndmask_b32_e32 v39, 0, v45, vcc
	v_cndmask_b32_e32 v40, 0, v46, vcc
	ds_write2_b32 v25, v19, v20 offset0:172 offset1:238
	v_cndmask_b32_e32 v19, 0, v21, vcc
	v_add_u32_e32 v21, 0x1800, v7
	ds_write2_b32 v7, v39, v40 offset0:132 offset1:198
	v_cndmask_b32_e32 v39, 0, v47, vcc
	v_cndmask_b32_e32 v40, 0, v48, vcc
	v_cndmask_b32_e32 v36, 0, v38, vcc
	v_cndmask_b32_e32 v32, 0, v34, vcc
	v_cndmask_b32_e32 v28, 0, v30, vcc
	v_cndmask_b32_e32 v24, 0, v26, vcc
	v_cndmask_b32_e32 v20, 0, v22, vcc
	ds_write2_b32 v21, v15, v16 offset0:180 offset1:246
	s_waitcnt vmcnt(3)
	v_cndmask_b32_e32 v15, 0, v17, vcc
	v_add_u32_e32 v17, 0x1c00, v7
	ds_write2_b32 v41, v39, v40 offset0:8 offset1:74
	ds_write2_b32 v37, v35, v36 offset0:16 offset1:82
	ds_write2_b32 v33, v31, v32 offset0:24 offset1:90
	ds_write2_b32 v29, v27, v28 offset0:32 offset1:98
	ds_write2_b32 v25, v23, v24 offset0:40 offset1:106
	ds_write2_b32 v21, v19, v20 offset0:48 offset1:114
	v_add_u32_e32 v36, s15, v11
	v_ashrrev_i32_e32 v37, 31, v36
	s_mul_i32 s6, s4, 0x16000
	v_add_u32_e32 v11, s6, v11
	s_waitcnt vmcnt(2)
	v_cndmask_b32_e32 v16, 0, v18, vcc
	ds_write2_b32 v17, v15, v16 offset0:56 offset1:122
	v_lshl_add_u64 v[18:19], s[8:9], 1, v[2:3]
	v_lshl_add_u64 v[38:39], v[36:37], 1, v[18:19]
	s_waitcnt vmcnt(1)
	v_cndmask_b32_e32 v0, 0, v0, vcc
	s_waitcnt vmcnt(0)
	v_cndmask_b32_e32 v14, 0, v14, vcc
	ds_write2_b32 v17, v0, v14 offset0:188 offset1:254
	s_waitcnt vmcnt(0) expcnt(0) lgkmcnt(0)
	ds_read2_b32 v[20:21], v4 offset0:33 offset1:41
	ds_read2_b32 v[22:23], v4 offset1:8
	ds_read2_b32 v[24:25], v4 offset0:66 offset1:74
	ds_read2_b32 v[26:27], v4 offset0:99 offset1:107
	ds_read2_b32 v[28:29], v4 offset0:132 offset1:140
	ds_read2_b32 v[30:31], v4 offset0:165 offset1:173
	ds_read2_b32 v[32:33], v4 offset0:198 offset1:206
	ds_read2_b32 v[34:35], v4 offset0:231 offset1:239
	s_waitcnt lgkmcnt(6)
	v_cvt_pk_bf16_f32 v14, v22, v20
	v_add_u32_e32 v20, 0x5800, v36
	s_waitcnt lgkmcnt(4)
	v_cvt_pk_bf16_f32 v15, v24, v26
	s_waitcnt lgkmcnt(2)
	v_cvt_pk_bf16_f32 v16, v28, v30
	s_waitcnt lgkmcnt(0)
	v_cvt_pk_bf16_f32 v17, v32, v34
	global_store_dwordx4 v[38:39], v[14:17], off
	v_add_u32_e32 v38, 0xb000, v36
	v_ashrrev_i32_e32 v39, 31, v38
	v_cvt_pk_bf16_f32 v14, v23, v21
	v_ashrrev_i32_e32 v21, 31, v20
	v_lshl_add_u64 v[20:21], v[20:21], 1, v[18:19]
	v_cvt_pk_bf16_f32 v15, v25, v27
	v_cvt_pk_bf16_f32 v16, v29, v31
	v_cvt_pk_bf16_f32 v17, v33, v35
	global_store_dwordx4 v[20:21], v[14:17], off
	ds_read2_b32 v[20:21], v4 offset0:16 offset1:24
	ds_read2_b32 v[22:23], v4 offset0:49 offset1:57
	ds_read2_b32 v[24:25], v4 offset0:82 offset1:90
	ds_read2_b32 v[26:27], v4 offset0:115 offset1:123
	ds_read2_b32 v[28:29], v4 offset0:148 offset1:156
	ds_read2_b32 v[30:31], v4 offset0:181 offset1:189
	ds_read2_b32 v[32:33], v4 offset0:214 offset1:222
	ds_read2_b32 v[34:35], v4 offset0:247 offset1:255
	s_waitcnt lgkmcnt(6)
	v_cvt_pk_bf16_f32 v14, v20, v22
	v_lshl_add_u64 v[38:39], v[38:39], 1, v[18:19]
	v_add_u32_e32 v20, 0x10800, v36
	s_waitcnt lgkmcnt(4)
	v_cvt_pk_bf16_f32 v15, v24, v26
	s_waitcnt lgkmcnt(2)
	v_cvt_pk_bf16_f32 v16, v28, v30
	s_waitcnt lgkmcnt(0)
	v_cvt_pk_bf16_f32 v17, v32, v34
	global_store_dwordx4 v[38:39], v[14:17], off
	s_nop 1
	v_cvt_pk_bf16_f32 v14, v21, v23
	v_ashrrev_i32_e32 v21, 31, v20
	v_lshl_add_u64 v[18:19], v[20:21], 1, v[18:19]
	v_cvt_pk_bf16_f32 v15, v25, v27
	v_cvt_pk_bf16_f32 v16, v29, v31
	v_cvt_pk_bf16_f32 v17, v33, v35
	global_store_dwordx4 v[18:19], v[14:17], off
	s_waitcnt vmcnt(0) expcnt(0) lgkmcnt(0)
	s_cbranch_scc0 .LBB0_227
	s_branch .LBB0_222

; #define LDSBAR() do { asm volatile("s_waitcnt lgkmcnt(0)" ::: "memory"); __builtin_amdgcn_s_barrier(); asm volatile("" ::: "memory"); } while (0)
; __device__ __forceinline__ void swa_block_task(const P& p, int task, unsigned char* sm, int tid) {
;     const int wave = tid >> 6, lane = tid & 63, fr = lane & 15, g = lane >> 4;
;     const bf16_t* Q = (const bf16_t*)(p.ws + WS_SWQ); const bf16_t* K = (const bf16_t*)(p.ws + WS_SWK); const bf16_t* VT = (const bf16_t*)(p.ws + WS_SWVT); bf16_t* Y = (bf16_t*)(p.ws + WS_A);
;     const int g4 = task & 3, qblk = (task >> 2) & 15, b = task >> 6;
;     const int Q0 = qblk * 128, qt = Q0 + wave * 16 + fr; const size_t qrow = (size_t)b * TLAT + qt;
;     AttnState st[4]; bf16x8 q0[4], q1[4];
; #pragma unroll
;     for (int hh = 0; hh < 4; ++hh) {
;         const int hq = g4 * 4 + hh;
;         st[hh].m = p.sink[hq]; st[hh].l = (g == 0) ? 1.f : 0.f;
; #pragma unroll
;         for (int dt = 0; dt < 4; ++dt) st[hh].o[dt] = (f32x4){0.f, 0.f, 0.f, 0.f};
;         const bf16_t* qp = Q + qrow * 1024 + hq * 64 + g * 8;
;         q0[hh] = *(const bf16x8*)qp; q1[hh] = *(const bf16x8*)(qp + 32);
;     }
;     const int cw0 = Q0 >= 128 ? 0 : (128 - Q0) / 32, cw1 = (Q0 + 256 <= TLAT) ? 11 : (TLAT - 1 - (Q0 - 128)) / 32;
;     const int nwin = cw1 - cw0 + 1, nch = nwin + 8;
;     const bool isk = tid < 256; const int lr = isk ? (tid >> 3) : ((tid - 256) >> 2), lp = isk ? (tid & 7) : (tid & 3);
;     auto gload = [&](int i) -> u32x4 {
;         const int tok0 = (i < nwin) ? (Q0 - 128 + 32 * (cw0 + i)) : (TLAT + 32 * (i - nwin));
;         if (isk) { const size_t row = (i < nwin) ? (size_t)b * TLAT + tok0 + lr : (size_t)MLAT + b * TCTX + 32 * (i - nwin) + lr;
;             return *(const u32x4*)(K + row * 256 + g4 * 64 + lp * 8); }
;         return *(const u32x4*)(VT + ((size_t)b * 256 + g4 * 64 + lr) * TT + tok0 + lp * 8);
;     };
;     auto lwrite = [&](int stage, const u32x4& v) {
;         unsigned char* sb = sm + stage * SW_STAGE;
;         if (isk) *(u32x4*)(sb + lr * 144 + lp * 16) = v; else *(u32x4*)(sb + SW_KB + lr * 80 + lp * 16) = v;
;     };
;     u32x4 R = gload(0);
;     lwrite(0, R);
;     if (nch > 1) R = gload(1);
;     LDSBAR();
.LBB0_265:
	s_or_b64 exec, exec, s[2:3]
	v_readlane_b32 s2, v254, 0
	v_mov_b32_e32 v0, v1
	v_readlane_b32 s3, v254, 1
	s_waitcnt lgkmcnt(0)
	s_barrier
	s_andn2_b64 vcc, exec, s[2:3]
	v_readfirstlane_b32 s2, v0
	s_cbranch_vccnz .LBB0_292
	s_load_dwordx2 s[10:11], s[92:93], s2 offset:0xa8
	s_nop 0
	s_load_dwordx2 s[2:3], s[92:93], s2 offset:0x90
	v_bfe_u32 v4, v146, 4, 2
	v_ashrrev_i32_e32 v0, 2, v146
	s_movk_i32 s8, 0x100
	s_waitcnt lgkmcnt(0)
	s_add_u32 s12, s10, 0xa800000
	v_and_b32_e32 v145, -16, v0
	v_lshlrev_b32_e32 v152, 4, v4
	v_mov_b32_e32 v153, v1
	v_add_u32_e32 v0, 0xffffff00, v146
	v_cmp_gt_i32_e64 s[8:9], s8, v146
	s_addc_u32 s13, s11, 0
	v_lshl_add_u64 v[2:3], s[10:11], 0, v[152:153]
	s_mov_b64 s[6:7], 0x7f00000
	v_lshrrev_b32_e32 v147, 2, v0
	v_cndmask_b32_e64 v0, 3, 7, s[8:9]
	v_lshlrev_b32_e32 v150, 3, v4
	v_mov_b32_e32 v151, v1
	v_lshl_add_u64 v[154:155], v[2:3], 0, s[6:7]
	s_add_u32 s14, s10, 0x9f00000
	v_and_b32_e32 v2, v0, v146
	v_and_b32_e32 v143, 15, v146
	v_cmp_eq_u32_e32 vcc, 0, v4
	s_addc_u32 s15, s11, 0
	v_lshlrev_b32_e32 v0, 3, v2
	v_lshlrev_b32_e32 v172, 4, v2
	v_lshlrev_b32_e32 v4, 2, v4
	v_lshl_add_u64 v[2:3], s[10:11], 0, v[150:151]
	s_mov_b64 s[10:11], 0x5b00000
	v_cndmask_b32_e64 v148, 0, 1.0, vcc
	s_movk_i32 s1, 0xff
	v_ashrrev_i32_e32 v156, 3, v146
	v_lshl_add_u64 v[158:159], v[2:3], 0, s[10:11]
	v_sub_u32_e32 v2, v4, v143
	v_cmp_lt_i32_e64 s[6:7], s1, v146
	v_cndmask_b32_e64 v153, v147, v156, s[8:9]
	v_ashrrev_i32_e32 v157, 31, v156
	v_mul_u32_u24_e32 v173, 0x90, v143
	v_mul_u32_u24_e32 v174, 0x50, v143
	v_mov_b32_e32 v149, v148
	v_sub_u32_e32 v151, v2, v145
	v_lshlrev_b32_e32 v0, 1, v0
	v_readlane_b32 s22, v254, 17
	v_readlane_b32 s23, v254, 20
	s_branch .LBB0_268
	s_nop 0
	s_nop 0
	s_nop 0
	s_nop 0
	s_nop 0
	s_nop 0
	s_nop 0
	s_nop 0
	s_nop 0
	s_nop 0
	s_nop 0
	s_nop 0
	s_nop 0
	s_nop 0

; __device__ __forceinline__ f32x4 mfma16(bf16x8 a, bf16x8 b, f32x4 c) { return __builtin_amdgcn_mfma_f32_16x16x32_bf16(a, b, c, 0, 0, 0); }
; __device__ __forceinline__ void dn_prep_task(const P& p, int task, unsigned char* sm, int tid) {
;     ...
;     {
;         const int which = wave >> 2, it = wave & 3, fr = lane & 15, g = lane >> 4;
;         const bf16_t* As = which ? qn_s : kn_s; float* Out = which ? QK : KK;
;         bf16x8 a[4];
; #pragma unroll
;         for (int ks = 0; ks < 4; ++ks) a[ks] = *(const bf16x8*)(As + (it * 16 + fr) * 136 + ks * 32 + g * 8);
; #pragma unroll
;         for (int jt = 0; jt < 4; ++jt) {
;             f32x4 acc = {0.f, 0.f, 0.f, 0.f};
; #pragma unroll
;             for (int ks = 0; ks < 4; ++ks) { const bf16x8 bb = *(const bf16x8*)(kn_s + (jt * 16 + fr) * 136 + ks * 32 + g * 8); acc = mfma16(a[ks], bb, acc); }
; #pragma unroll
;             for (int r = 0; r < 4; ++r) Out[(it * 16 + 4 * g + r) * 65 + jt * 16 + fr] = acc[r];
;         }
;     }
;     __syncthreads();
;     const float* gc = gc_s + dir * 64; const float* be = be_s + dir * 64; float* L = Ls + dir * 4096;
;     const size_t dt = (size_t)task * 2 + dir;
;     {
;         const int cp = t2 >> 2, s0 = (t2 & 3) * 16; const int ctok = dir ? 63 - cp : cp; const float gcc = gc[cp], bec = be[cp];
; #pragma unroll
;         for (int i = 0; i < 16; ++i) { const int sp = s0 + i, stok = dir ? 63 - sp : sp; float v = 0.f; if (cp > sp) v = bec * KK[ctok * 65 + stok] * __expf(gcc - gc[sp]); L[cp * 64 + sp] = v; }
.Lpl_b:
	s_or_b64 exec, exec, s[82:83]
	s_waitcnt vmcnt(4)
	ds_write_b128 v89, v[38:41]
	ds_write_b128 v89, v[34:37] offset:16
	s_waitcnt vmcnt(2)
	ds_write_b128 v89, v[46:49] offset:17408
	ds_write_b128 v89, v[42:45] offset:17424
	s_waitcnt vmcnt(0)
	ds_write_b128 v90, v[56:59]
	ds_write_b128 v90, v[52:55] offset:16
	s_waitcnt lgkmcnt(0)
	s_barrier
	ds_read_b128 v[2:5], v148
	ds_read_b128 v[26:29], v148 offset:64
	ds_read_b128 v[30:33], v148 offset:128
	ds_read_b128 v[34:37], v148 offset:192
	ds_read_b128 v[40:43], v149
	ds_read_b128 v[44:47], v149 offset:64
	ds_read_b128 v[48:51], v149 offset:128
	ds_read_b128 v[52:55], v149 offset:192
	ds_read_b128 v[56:59], v149 offset:4352
	ds_read_b128 v[60:63], v149 offset:4416
	ds_read_b128 v[64:67], v149 offset:4480
	ds_read_b128 v[68:71], v149 offset:4544
	ds_read_b128 v[72:75], v149 offset:8704
	ds_read_b128 v[76:79], v149 offset:8768
	ds_read_b128 v[80:83], v149 offset:8832
	ds_read_b128 v[84:87], v149 offset:8896
	ds_read_b128 v[152:155], v149 offset:13056
	ds_read_b128 v[156:159], v149 offset:13120
	ds_read_b128 v[160:163], v149 offset:13184
	ds_read_b128 v[164:167], v149 offset:13248
	s_waitcnt lgkmcnt(0)
	v_mfma_f32_16x16x32_bf16 v[168:171], v[2:5], v[40:43], 0
	v_mfma_f32_16x16x32_bf16 v[172:175], v[2:5], v[56:59], 0
	v_mfma_f32_16x16x32_bf16 v[176:179], v[2:5], v[72:75], 0
	v_mfma_f32_16x16x32_bf16 v[180:183], v[2:5], v[152:155], 0
	v_mfma_f32_16x16x32_bf16 v[168:171], v[26:29], v[44:47], v[168:171]
	v_mfma_f32_16x16x32_bf16 v[172:175], v[26:29], v[60:63], v[172:175]
	v_mfma_f32_16x16x32_bf16 v[176:179], v[26:29], v[76:79], v[176:179]
	v_mfma_f32_16x16x32_bf16 v[180:183], v[26:29], v[156:159], v[180:183]
	v_mfma_f32_16x16x32_bf16 v[168:171], v[30:33], v[48:51], v[168:171]
	v_mfma_f32_16x16x32_bf16 v[172:175], v[30:33], v[64:67], v[172:175]
	v_mfma_f32_16x16x32_bf16 v[176:179], v[30:33], v[80:83], v[176:179]
	v_mfma_f32_16x16x32_bf16 v[180:183], v[30:33], v[160:163], v[180:183]
	v_mfma_f32_16x16x32_bf16 v[168:171], v[34:37], v[52:55], v[168:171]
	v_mfma_f32_16x16x32_bf16 v[172:175], v[34:37], v[68:71], v[172:175]
	v_mfma_f32_16x16x32_bf16 v[176:179], v[34:37], v[84:87], v[176:179]
	v_mfma_f32_16x16x32_bf16 v[180:183], v[34:37], v[164:167], v[180:183]
	s_nop 7
	ds_write_b32 v150, v168
	ds_write_b32 v150, v169 offset:260
	ds_write_b32 v150, v170 offset:520
	ds_write_b32 v150, v171 offset:780
	ds_write_b32 v150, v172 offset:64
	ds_write_b32 v150, v173 offset:324
	ds_write_b32 v150, v174 offset:584
	ds_write_b32 v150, v175 offset:844
	ds_write_b32 v150, v176 offset:128
	ds_write_b32 v150, v177 offset:388
	ds_write_b32 v150, v178 offset:648
	ds_write_b32 v150, v179 offset:908
	s_nop 7
	ds_write_b32 v150, v180 offset:192
	ds_write_b32 v150, v181 offset:452
	ds_write_b32 v150, v182 offset:712
	ds_write_b32 v150, v183 offset:972
	s_waitcnt lgkmcnt(0)
	s_barrier
	ds_read_b32 v2, v121
	ds_read_b32 v3, v122
	ds_read_b128 v[24:27], v123
	ds_read_b128 v[28:31], v123 offset:16
	ds_read_b128 v[32:35], v123 offset:32
	ds_read_b128 v[36:39], v123 offset:48
	ds_read_b32 v40, v95 offset:34816
	ds_read_b32 v41, v97 offset:34816
	ds_read_b32 v42, v98 offset:34816
	ds_read_b32 v43, v99 offset:34816
	ds_read_b32 v44, v100 offset:34816
	ds_read_b32 v45, v101 offset:34816
	ds_read_b32 v46, v102 offset:34816
	ds_read_b32 v47, v103 offset:34816
	ds_read_b32 v48, v104 offset:34816
	ds_read_b32 v49, v105 offset:34816
	ds_read_b32 v50, v106 offset:34816
	ds_read_b32 v51, v107 offset:34816
	ds_read_b32 v52, v108 offset:34816
	ds_read_b32 v53, v109 offset:34816
	ds_read_b32 v54, v110 offset:34816
	ds_read_b32 v55, v111 offset:34816
	v_bfe_u32 v56, v144, 2, 6
	v_and_b32_e32 v57, 3, v144
	v_lshlrev_b32_e32 v57, 4, v57
	v_sub_u32_e32 v56, v56, v57
	s_waitcnt lgkmcnt(0)
	v_sub_f32_e32 v24, v2, v24
	v_sub_f32_e32 v25, v2, v25
	v_sub_f32_e32 v26, v2, v26
	v_sub_f32_e32 v27, v2, v27
	v_sub_f32_e32 v28, v2, v28
	v_sub_f32_e32 v29, v2, v29
	v_sub_f32_e32 v30, v2, v30
	v_sub_f32_e32 v31, v2, v31
	v_sub_f32_e32 v32, v2, v32
	v_sub_f32_e32 v33, v2, v33
	v_sub_f32_e32 v34, v2, v34
	v_sub_f32_e32 v35, v2, v35
	v_sub_f32_e32 v36, v2, v36
	v_sub_f32_e32 v37, v2, v37
	v_sub_f32_e32 v38, v2, v38
	v_sub_f32_e32 v39, v2, v39
	v_mul_f32_e32 v24, 0x3fb8aa3b, v24
	v_mul_f32_e32 v25, 0x3fb8aa3b, v25
	v_mul_f32_e32 v26, 0x3fb8aa3b, v26
	v_mul_f32_e32 v27, 0x3fb8aa3b, v27
	v_mul_f32_e32 v28, 0x3fb8aa3b, v28
	v_mul_f32_e32 v29, 0x3fb8aa3b, v29
	v_mul_f32_e32 v30, 0x3fb8aa3b, v30
	v_mul_f32_e32 v31, 0x3fb8aa3b, v31
	v_mul_f32_e32 v32, 0x3fb8aa3b, v32
	v_mul_f32_e32 v33, 0x3fb8aa3b, v33
	v_mul_f32_e32 v34, 0x3fb8aa3b, v34
	v_mul_f32_e32 v35, 0x3fb8aa3b, v35
	v_mul_f32_e32 v36, 0x3fb8aa3b, v36
	v_mul_f32_e32 v37, 0x3fb8aa3b, v37
	v_mul_f32_e32 v38, 0x3fb8aa3b, v38
	v_mul_f32_e32 v39, 0x3fb8aa3b, v39
	v_exp_f32_e32 v24, v24
	v_exp_f32_e32 v25, v25
	v_exp_f32_e32 v26, v26
	v_exp_f32_e32 v27, v27
	v_exp_f32_e32 v28, v28
	v_exp_f32_e32 v29, v29
	v_exp_f32_e32 v30, v30
	v_exp_f32_e32 v31, v31
	v_exp_f32_e32 v32, v32
	v_exp_f32_e32 v33, v33
	v_exp_f32_e32 v34, v34
	v_exp_f32_e32 v35, v35
	v_exp_f32_e32 v36, v36
	v_exp_f32_e32 v37, v37
	v_exp_f32_e32 v38, v38
	v_exp_f32_e32 v39, v39
	v_mul_f32_e32 v40, v3, v40
	v_mul_f32_e32 v41, v3, v41
	v_mul_f32_e32 v42, v3, v42
	v_mul_f32_e32 v43, v3, v43
	v_mul_f32_e32 v44, v3, v44
	v_mul_f32_e32 v45, v3, v45
	v_mul_f32_e32 v46, v3, v46
	v_mul_f32_e32 v47, v3, v47
	v_mul_f32_e32 v48, v3, v48
	v_mul_f32_e32 v49, v3, v49
	v_mul_f32_e32 v50, v3, v50
	v_mul_f32_e32 v51, v3, v51
	v_mul_f32_e32 v52, v3, v52
	v_mul_f32_e32 v53, v3, v53
	v_mul_f32_e32 v54, v3, v54
	v_mul_f32_e32 v55, v3, v55
	v_mul_f32_e32 v40, v40, v24
; __device__ __forceinline__ void dn_prep_task(const P& p, int task, unsigned char* sm, int tid) {
;     ...
;         const int cp = t2 >> 2, s0 = (t2 & 3) * 16; const int ctok = dir ? 63 - cp : cp; const float gcc = gc[cp], bec = be[cp];
; #pragma unroll
;         for (int i = 0; i < 16; ++i) { const int sp = s0 + i, stok = dir ? 63 - sp : sp; float v = 0.f; if (cp > sp) v = bec * KK[ctok * 65 + stok] * __expf(gcc - gc[sp]); L[cp * 64 + sp] = v; }
;         const int c = t2 >> 2, c_p = dir ? 63 - c : c; const float gq = gc[c_p];
;         float qv[16];
; #pragma unroll
;         for (int i = 0; i < 16; ++i) { const int s = s0 + i, s_p = dir ? 63 - s : s; qv[i] = (c_p >= s_p) ? QK[c * 65 + s] * SCALE_DK * __expf(gq - gc[s_p]) : 0.f; }
	v_mul_f32_e32 v41, v41, v25
	v_mul_f32_e32 v42, v42, v26
	v_mul_f32_e32 v43, v43, v27
	v_mul_f32_e32 v44, v44, v28
	v_mul_f32_e32 v45, v45, v29
	v_mul_f32_e32 v46, v46, v30
	v_mul_f32_e32 v47, v47, v31
	v_mul_f32_e32 v48, v48, v32
	v_mul_f32_e32 v49, v49, v33
	v_mul_f32_e32 v50, v50, v34
	v_mul_f32_e32 v51, v51, v35
	v_mul_f32_e32 v52, v52, v36
	v_mul_f32_e32 v53, v53, v37
	v_mul_f32_e32 v54, v54, v38
	v_mul_f32_e32 v55, v55, v39
	v_cmp_lt_i32_e32 vcc, 0, v56
	v_cndmask_b32_e32 v40, 0, v40, vcc
	v_cmp_lt_i32_e32 vcc, 1, v56
	v_cndmask_b32_e32 v41, 0, v41, vcc
	v_cmp_lt_i32_e32 vcc, 2, v56
	v_cndmask_b32_e32 v42, 0, v42, vcc
	v_cmp_lt_i32_e32 vcc, 3, v56
	v_cndmask_b32_e32 v43, 0, v43, vcc
	v_cmp_lt_i32_e32 vcc, 4, v56
	v_cndmask_b32_e32 v44, 0, v44, vcc
	v_cmp_lt_i32_e32 vcc, 5, v56
	v_cndmask_b32_e32 v45, 0, v45, vcc
	v_cmp_lt_i32_e32 vcc, 6, v56
	v_cndmask_b32_e32 v46, 0, v46, vcc
	v_cmp_lt_i32_e32 vcc, 7, v56
	v_cndmask_b32_e32 v47, 0, v47, vcc
	v_cmp_lt_i32_e32 vcc, 8, v56
	v_cndmask_b32_e32 v48, 0, v48, vcc
	v_cmp_lt_i32_e32 vcc, 9, v56
	v_cndmask_b32_e32 v49, 0, v49, vcc
	v_cmp_lt_i32_e32 vcc, 10, v56
	v_cndmask_b32_e32 v50, 0, v50, vcc
	v_cmp_lt_i32_e32 vcc, 11, v56
	v_cndmask_b32_e32 v51, 0, v51, vcc
	v_cmp_lt_i32_e32 vcc, 12, v56
	v_cndmask_b32_e32 v52, 0, v52, vcc
	v_cmp_lt_i32_e32 vcc, 13, v56
	v_cndmask_b32_e32 v53, 0, v53, vcc
	v_cmp_lt_i32_e32 vcc, 14, v56
	v_cndmask_b32_e32 v54, 0, v54, vcc
	v_cmp_lt_i32_e32 vcc, 15, v56
	v_cndmask_b32_e32 v55, 0, v55, vcc
	ds_write_b128 v96, v[40:43]
	ds_write_b128 v96, v[44:47] offset:16
	ds_write_b128 v96, v[48:51] offset:32
	ds_write_b128 v96, v[52:55] offset:48
	v_mov_b32_e32 v4, 0
	v_mov_b32_e32 v5, 0
	s_waitcnt lgkmcnt(14)
	ds_read_b32 v2, v124
	ds_read_b32 v40, v125
	ds_read_b32 v41, v126
	ds_read_b32 v42, v127
	ds_read_b32 v43, v128
	ds_read_b32 v44, v129
	ds_read_b32 v45, v130
	ds_read_b32 v46, v131
	ds_read_b32 v47, v132
	ds_read_b32 v48, v133
	ds_read_b32 v49, v134
	ds_read_b32 v50, v135
	ds_read_b32 v51, v136
	ds_read_b32 v52, v137
	ds_read_b32 v53, v143
	ds_read_b32 v54, v145
	ds_read_b32 v55, v146
	ds_read_b32 v56, v112 offset:51456
	ds_read_b32 v57, v112 offset:51460
	ds_read_b32 v58, v112 offset:51464
	ds_read_b32 v59, v112 offset:51468
	ds_read_b32 v60, v112 offset:51472
	ds_read_b32 v61, v112 offset:51476
	ds_read_b32 v62, v112 offset:51480
	ds_read_b32 v63, v112 offset:51484
	ds_read_b32 v64, v112 offset:51488
	ds_read_b32 v65, v112 offset:51492
	ds_read_b32 v66, v112 offset:51496
	ds_read_b32 v67, v112 offset:51500
	ds_read_b32 v68, v112 offset:51504
	ds_read_b32 v69, v112 offset:51508
	ds_read_b32 v70, v112 offset:51512
	ds_read_b32 v71, v112 offset:51516
	s_waitcnt lgkmcnt(0)
	v_sub_f32_e32 v40, v2, v40
	v_sub_f32_e32 v41, v2, v41
	v_sub_f32_e32 v42, v2, v42
	v_sub_f32_e32 v43, v2, v43
	v_sub_f32_e32 v44, v2, v44
	v_sub_f32_e32 v45, v2, v45
	v_sub_f32_e32 v46, v2, v46
	v_sub_f32_e32 v47, v2, v47
	v_sub_f32_e32 v48, v2, v48
	v_sub_f32_e32 v49, v2, v49
	v_sub_f32_e32 v50, v2, v50
	v_sub_f32_e32 v51, v2, v51
	v_sub_f32_e32 v52, v2, v52
	v_sub_f32_e32 v53, v2, v53
	v_sub_f32_e32 v54, v2, v54
	v_sub_f32_e32 v55, v2, v55
	v_mul_f32_e32 v40, 0x3fb8aa3b, v40
	v_mul_f32_e32 v41, 0x3fb8aa3b, v41
	v_mul_f32_e32 v42, 0x3fb8aa3b, v42
	v_mul_f32_e32 v43, 0x3fb8aa3b, v43
	v_mul_f32_e32 v44, 0x3fb8aa3b, v44
	v_mul_f32_e32 v45, 0x3fb8aa3b, v45
	v_mul_f32_e32 v46, 0x3fb8aa3b, v46
	v_mul_f32_e32 v47, 0x3fb8aa3b, v47
	v_mul_f32_e32 v48, 0x3fb8aa3b, v48
	v_mul_f32_e32 v49, 0x3fb8aa3b, v49
	v_mul_f32_e32 v50, 0x3fb8aa3b, v50
	v_mul_f32_e32 v51, 0x3fb8aa3b, v51
	v_mul_f32_e32 v52, 0x3fb8aa3b, v52
	v_mul_f32_e32 v53, 0x3fb8aa3b, v53
	v_mul_f32_e32 v54, 0x3fb8aa3b, v54
	v_mul_f32_e32 v55, 0x3fb8aa3b, v55
	v_exp_f32_e32 v40, v40
	v_exp_f32_e32 v41, v41
	v_exp_f32_e32 v42, v42
	v_exp_f32_e32 v43, v43
	v_exp_f32_e32 v44, v44
	v_exp_f32_e32 v45, v45
	v_exp_f32_e32 v46, v46
	v_exp_f32_e32 v47, v47
	v_exp_f32_e32 v48, v48
	v_exp_f32_e32 v49, v49
	v_exp_f32_e32 v50, v50
	v_exp_f32_e32 v51, v51
	v_exp_f32_e32 v52, v52
	v_exp_f32_e32 v53, v53
	v_exp_f32_e32 v54, v54
	v_exp_f32_e32 v55, v55
	v_mul_f32_e32 v56, 0x3db504f3, v56
	v_mul_f32_e32 v57, 0x3db504f3, v57
	v_mul_f32_e32 v58, 0x3db504f3, v58
	v_mul_f32_e32 v59, 0x3db504f3, v59
	v_mul_f32_e32 v60, 0x3db504f3, v60
	v_mul_f32_e32 v61, 0x3db504f3, v61
	v_mul_f32_e32 v62, 0x3db504f3, v62
	v_mul_f32_e32 v63, 0x3db504f3, v63
	v_mul_f32_e32 v64, 0x3db504f3, v64
	v_mul_f32_e32 v65, 0x3db504f3, v65
	v_mul_f32_e32 v66, 0x3db504f3, v66
	v_mul_f32_e32 v67, 0x3db504f3, v67
	v_mul_f32_e32 v68, 0x3db504f3, v68
	v_mul_f32_e32 v69, 0x3db504f3, v69
	v_mul_f32_e32 v70, 0x3db504f3, v70
	v_mul_f32_e32 v71, 0x3db504f3, v71
	v_mul_f32_e32 v56, v56, v40
	v_mul_f32_e32 v57, v57, v41
	v_mul_f32_e32 v58, v58, v42
	v_mul_f32_e32 v59, v59, v43
	v_mul_f32_e32 v60, v60, v44
	v_mul_f32_e32 v61, v61, v45
	v_mul_f32_e32 v62, v62, v46
	v_mul_f32_e32 v63, v63, v47
	v_mul_f32_e32 v64, v64, v48
	v_mul_f32_e32 v65, v65, v49
	v_mul_f32_e32 v66, v66, v50
	v_mul_f32_e32 v67, v67, v51
	v_mul_f32_e32 v68, v68, v52
	v_mul_f32_e32 v69, v69, v53
	v_mul_f32_e32 v70, v70, v54
	v_mul_f32_e32 v71, v71, v55
	v_cndmask_b32_e64 v4, 0, v56, s[88:89]
	v_cndmask_b32_e64 v5, 0, v57, s[90:91]
	v_cndmask_b32_e64 v3, 0, v58, s[92:93]
	v_cndmask_b32_e64 v7, 0, v59, s[94:95]
	v_cndmask_b32_e64 v6, 0, v60, s[84:85]
	v_cndmask_b32_e64 v26, 0, v61, s[6:7]
	v_cndmask_b32_e64 v25, 0, v62, s[8:9]
	v_cndmask_b32_e64 v28, 0, v63, s[10:11]
	v_cndmask_b32_e64 v27, 0, v64, s[12:13]
	v_cndmask_b32_e64 v30, 0, v65, s[14:15]
	v_cndmask_b32_e64 v29, 0, v66, s[16:17]
	v_cndmask_b32_e64 v32, 0, v67, s[18:19]
	v_cndmask_b32_e64 v31, 0, v68, s[20:21]
	v_cndmask_b32_e64 v34, 0, v69, s[22:23]
	v_cndmask_b32_e64 v33, 0, v70, s[24:25]
	v_cndmask_b32_e64 v35, 0, v71, s[26:27]

; __device__ __forceinline__ void scan_gload(ScanRegs& R, const P& p, int step, int b, int h, int dir, int es, int t) {
;     int task; const int m0 = scan_m0(step, b, dir, task, h); const size_t dt = (size_t)task * 2 + dir;
;     const u32x4* negw = (const u32x4*)((const bf16_t*)(p.ws + WS_NEGW) + dt * 8192);
;     const u32x4* qk = (const u32x4*)((const bf16_t*)(p.ws + WS_QKC) + dt * 4096);
;     const u32x4* knT = (const u32x4*)((const bf16_t*)(p.ws + WS_KNT) + (size_t)task * 8192);
;     const u32x4* uT = (const u32x4*)((const bf16_t*)(p.ws + WS_UT) + dt * 8192 + es * 32 * 64);
;     const u32x4* rscs = (const u32x4*)((const float*)(p.ws + WS_RSCS) + dt * 256);
;     const bf16_t* qn = (const bf16_t*)(p.ws + WS_QN) + (size_t)m0 * 512 + h * 128;
; #pragma unroll
;     for (int i = 0; i < 2; ++i) { const int pp = t + 512 * i; R.a[i] = negw[pp]; R.b[i] = *(const u32x4*)(qn + (size_t)(pp >> 4) * 512 + (pp & 15) * 8); R.d[i] = knT[pp]; }
;     R.c = qk[t];
;     R.e = uT[t & 255];
;     R.f = rscs[t < 33 ? t : 0];
; }
; __device__ __forceinline__ void scan_lwrite(unsigned char* sb, const ScanRegs& R, int t) {
; #pragma unroll
;     for (int i = 0; i < 2; ++i) { const int pp = t + 512 * i;
;         *(u32x4*)(sb + (pp >> 4) * 272 + (pp & 15) * 16) = R.a[i];
;         *(u32x4*)(sb + SC_QN + (pp >> 4) * 272 + (pp & 15) * 16) = R.b[i];
;         *(u32x4*)(sb + SC_KNT + (pp >> 3) * 144 + (pp & 7) * 16) = R.d[i]; }
;     *(u32x4*)(sb + SC_QK + (t >> 3) * 144 + (t & 7) * 16) = R.c;
;     if (t < 256) *(u32x4*)(sb + SC_UT + (t >> 3) * 144 + (t & 7) * 16) = R.e;
;     if (t < 33) *(u32x4*)(sb + SC_RS + t * 16) = R.f;
; }
; __device__ __forceinline__ void dn_scan_task(const P& p, int st, unsigned char* sm, int tid) {
;     const int combo = (st & 7) + 8 * (st >> 5), es = (st >> 3) & 3;
;     const int dir = combo & 1, h = (combo >> 1) & 3, b = combo >> 3;
;     const int wave = tid >> 6, lane = tid & 63, fr = lane & 15, g = lane >> 4;
;     bf16_t* ST = (bf16_t*)sm;
;     bf16_t* VT = ST + 32 * 136;
;     bf16_t* VS = VT + 32 * 72;
;     const int ct = wave & 3, en = wave >> 2, e0 = es * 32 + en * 16, kt0 = 2 * (wave & 3);
;     f32x4 S0 = {0.f, 0.f, 0.f, 0.f}, S1 = {0.f, 0.f, 0.f, 0.f};
;     for (int i = tid; i < 32 * 136 / 2; i += NTHREADS) ((unsigned*)ST)[i] = 0u;
;     float* O = (float*)(p.ws + (dir ? WS_KN : WS_O));
;     ScanRegs R;
.LBB0_723:
	s_or_b64 exec, exec, s[18:19]
	s_and_b64 s[18:19], s[16:17], exec
	s_mov_b32 s18, 0x13a00000
	s_cselect_b32 s18, s18, 0x11300000
	s_add_u32 s42, s2, s18
	s_addc_u32 s43, s3, 0
	s_add_i32 s19, s64, 1
	s_lshl_b32 s18, s19, 6
	s_or_b32 s19, s19, s25
	s_lshl_b32 s19, s19, 2
	s_or_b32 s20, s19, s23
	s_ashr_i32 s21, s20, 31
	s_or_b32 s18, s24, s18
	s_lshl_b64 s[30:31], s[20:21], 1
	s_or_b64 s[30:31], s[30:31], s[64:65]
	s_ashr_i32 s19, s18, 31
	s_lshl_b64 s[34:35], s[30:31], 13
	s_lshl_b64 s[20:21], s[20:21], 14
	s_lshl_b64 s[18:19], s[18:19], 10
	s_add_u32 s40, s12, s18
	s_addc_u32 s19, s13, s19
	s_lshl_b32 s18, s29, 1
	s_add_u32 s40, s40, s18
	s_addc_u32 s41, s19, 0
	v_lshl_add_u64 v[18:19], s[40:41], 0, v[0:1]
	s_lshl_b64 s[40:41], s[30:31], 14
	v_lshl_add_u64 v[10:11], v[60:61], 0, s[40:41]
	v_lshl_add_u64 v[20:21], v[62:63], 0, s[20:21]
	s_lshl_b64 s[20:21], s[30:31], 10
	v_add_co_u32_e32 v14, vcc, s63, v10
	s_add_u32 s19, s14, s40
	s_nop 0
	v_addc_co_u32_e32 v15, vcc, 0, v11, vcc
	s_addc_u32 s31, s15, s41
	s_lshl_b32 s30, s28, 1
	v_add_co_u32_e32 v22, vcc, s63, v20
	s_add_u32 s40, s19, s30
	v_lshl_add_u64 v[6:7], v[18:19], 0, v[46:47]
	v_lshl_add_u64 v[18:19], v[18:19], 0, v[48:49]
	v_addc_co_u32_e32 v23, vcc, 0, v21, vcc
	s_addc_u32 s41, s31, 0
	v_lshl_add_u64 v[28:29], v[50:51], 0, s[34:35]
	global_load_dwordx4 v[2:5], v[10:11], off
	s_nop 0
	global_load_dwordx4 v[6:9], v[6:7], off
	s_nop 0
	global_load_dwordx4 v[10:13], v[20:21], off
	s_nop 0
	global_load_dwordx4 v[14:17], v[14:15], off
	s_nop 0
	global_load_dwordx4 v[18:21], v[18:19], off
	s_nop 0
	global_load_dwordx4 v[22:25], v[22:23], off
	v_mov_b32_e32 v65, v1
	global_load_dwordx4 v[30:33], v26, s[40:41]
	v_lshl_add_u64 v[26:27], v[54:55], 0, s[20:21]
	global_load_dwordx4 v[34:37], v[28:29], off
	global_load_dwordx4 v[38:41], v[26:27], off
	s_lshl_b32 s21, s26, 11
	s_addk_i32 s21, 0xff00
	s_lshl_b32 s26, s29, 2
	v_lshl_add_u32 v26, s27, 5, v53
	s_add_u32 s26, s42, s26
	v_ashrrev_i32_e32 v27, 31, v26
	s_addc_u32 s27, s43, 0
	s_waitcnt lgkmcnt(0)
	s_barrier
	v_lshl_add_u64 v[26:27], v[26:27], 2, s[26:27]
	s_mov_b32 s19, s65
	s_mov_b32 s31, s65
	v_lshl_add_u64 v[66:67], v[26:27], 0, v[64:65]
	v_mov_b32_e32 v26, 0
	s_mov_b32 s20, 2
	v_lshl_add_u64 v[68:69], v[56:57], 0, s[18:19]
	v_lshl_add_u64 v[70:71], v[58:59], 0, s[30:31]
	s_mov_b32 s26, -2
	v_mov_b32_e32 v27, v26
	v_mov_b32_e32 v28, v26
	v_mov_b32_e32 v29, v26
	v_mov_b32_e32 v42, v26
	v_mov_b32_e32 v43, v26
	v_mov_b32_e32 v44, v26
	v_mov_b32_e32 v45, v26
	s_branch .LBB0_725
	s_nop 0
	s_nop 0
	s_nop 0
	s_nop 0
	s_nop 0
